# P6 key-norm maxima tail: the 16 serial row loads issued up front and the lane reductions batched (tail of half the workgroups before the P6 seam)
# speedup vs baseline: 1.0062x; 1.0054x over previous
.LBB0_1300:
	v_mov_b32_e32 v16, v11
	v_ashrrev_i32_e32 v17, 31, v11
	v_lshlrev_b64 v[16:17], 10, v[16:17]
	v_lshl_add_u64 v[26:27], v[6:7], 0, v[16:17]
	v_lshl_add_u64 v[28:29], 0, 11, v[26:27]
	global_load_dwordx4 v[32:35], v[28:29], off offset:-2048
	v_lshl_add_u64 v[28:29], 1, 11, v[26:27]
	global_load_dwordx4 v[36:39], v[28:29], off offset:-2048
	v_lshl_add_u64 v[28:29], 2, 11, v[26:27]
	global_load_dwordx4 v[40:43], v[28:29], off offset:-2048
	v_lshl_add_u64 v[28:29], 3, 11, v[26:27]
	global_load_dwordx4 v[44:47], v[28:29], off offset:-2048
	v_lshl_add_u64 v[28:29], 4, 11, v[26:27]
	global_load_dwordx4 v[48:51], v[28:29], off offset:-2048
	v_lshl_add_u64 v[28:29], 5, 11, v[26:27]
	global_load_dwordx4 v[52:55], v[28:29], off offset:-2048
	v_lshl_add_u64 v[28:29], 6, 11, v[26:27]
	global_load_dwordx4 v[56:59], v[28:29], off offset:-2048
	v_lshl_add_u64 v[28:29], 7, 11, v[26:27]
	global_load_dwordx4 v[60:63], v[28:29], off offset:-2048
	v_lshl_add_u64 v[28:29], 8, 11, v[26:27]
	global_load_dwordx4 v[64:67], v[28:29], off offset:-2048
	v_lshl_add_u64 v[28:29], 9, 11, v[26:27]
	global_load_dwordx4 v[68:71], v[28:29], off offset:-2048
	v_lshl_add_u64 v[28:29], 10, 11, v[26:27]
	global_load_dwordx4 v[72:75], v[28:29], off offset:-2048
	v_lshl_add_u64 v[28:29], 11, 11, v[26:27]
	global_load_dwordx4 v[76:79], v[28:29], off offset:-2048
	v_lshl_add_u64 v[28:29], 12, 11, v[26:27]
	global_load_dwordx4 v[80:83], v[28:29], off offset:-2048
	v_lshl_add_u64 v[28:29], 13, 11, v[26:27]
	global_load_dwordx4 v[84:87], v[28:29], off offset:-2048
	v_lshl_add_u64 v[28:29], 14, 11, v[26:27]
	global_load_dwordx4 v[88:91], v[28:29], off offset:-2048
	v_lshl_add_u64 v[28:29], 15, 11, v[26:27]
	global_load_dwordx4 v[92:95], v[28:29], off offset:-2048
	v_max_f32_e32 v14, v14, v14
	s_waitcnt vmcnt(15)
	v_and_b32_e32 v21, 0xffff0000, v32
	v_lshlrev_b32_e32 v20, 16, v32
	v_and_b32_e32 v23, 0xffff0000, v33
	v_lshlrev_b32_e32 v22, 16, v33
	v_and_b32_e32 v17, 0xffff0000, v34
	v_lshlrev_b32_e32 v16, 16, v34
	v_and_b32_e32 v25, 0xffff0000, v35
	v_lshlrev_b32_e32 v24, 16, v35
	v_pk_mul_f32 v[18:19], v[20:21], v[20:21]
	v_pk_mul_f32 v[20:21], v[22:23], v[22:23]
	v_add_f32_e32 v18, v18, v19
	v_add_f32_e32 v18, v18, v20
	v_pk_mul_f32 v[16:17], v[16:17], v[16:17]
	v_add_f32_e32 v18, v18, v21
	v_add_f32_e32 v16, v18, v16
	v_pk_mul_f32 v[22:23], v[24:25], v[24:25]
	v_add_f32_e32 v16, v16, v17
	v_add_f32_e32 v16, v16, v22
	v_add_f32_e32 v96, v16, v23
	s_waitcnt vmcnt(14)
	v_and_b32_e32 v21, 0xffff0000, v36
	v_lshlrev_b32_e32 v20, 16, v36
	v_and_b32_e32 v23, 0xffff0000, v37
	v_lshlrev_b32_e32 v22, 16, v37
	v_and_b32_e32 v17, 0xffff0000, v38
	v_lshlrev_b32_e32 v16, 16, v38
	v_and_b32_e32 v25, 0xffff0000, v39
	v_lshlrev_b32_e32 v24, 16, v39
	v_pk_mul_f32 v[18:19], v[20:21], v[20:21]
	v_pk_mul_f32 v[20:21], v[22:23], v[22:23]
	v_add_f32_e32 v18, v18, v19
	v_add_f32_e32 v18, v18, v20
	v_pk_mul_f32 v[16:17], v[16:17], v[16:17]
	v_add_f32_e32 v18, v18, v21
	v_add_f32_e32 v16, v18, v16
	v_pk_mul_f32 v[22:23], v[24:25], v[24:25]
	v_add_f32_e32 v16, v16, v17
	v_add_f32_e32 v16, v16, v22
	v_add_f32_e32 v97, v16, v23
	s_waitcnt vmcnt(13)
	v_and_b32_e32 v21, 0xffff0000, v40
	v_lshlrev_b32_e32 v20, 16, v40
	v_and_b32_e32 v23, 0xffff0000, v41
	v_lshlrev_b32_e32 v22, 16, v41
	v_and_b32_e32 v17, 0xffff0000, v42
	v_lshlrev_b32_e32 v16, 16, v42
	v_and_b32_e32 v25, 0xffff0000, v43
	v_lshlrev_b32_e32 v24, 16, v43
	v_pk_mul_f32 v[18:19], v[20:21], v[20:21]
	v_pk_mul_f32 v[20:21], v[22:23], v[22:23]
	v_add_f32_e32 v18, v18, v19
	v_add_f32_e32 v18, v18, v20
	v_pk_mul_f32 v[16:17], v[16:17], v[16:17]
	v_add_f32_e32 v18, v18, v21
	v_add_f32_e32 v16, v18, v16
	v_pk_mul_f32 v[22:23], v[24:25], v[24:25]
	v_add_f32_e32 v16, v16, v17
	v_add_f32_e32 v16, v16, v22
	v_add_f32_e32 v98, v16, v23
	s_waitcnt vmcnt(12)
	v_and_b32_e32 v21, 0xffff0000, v44
	v_lshlrev_b32_e32 v20, 16, v44
	v_and_b32_e32 v23, 0xffff0000, v45
	v_lshlrev_b32_e32 v22, 16, v45
	v_and_b32_e32 v17, 0xffff0000, v46
	v_lshlrev_b32_e32 v16, 16, v46
	v_and_b32_e32 v25, 0xffff0000, v47
	v_lshlrev_b32_e32 v24, 16, v47
	v_pk_mul_f32 v[18:19], v[20:21], v[20:21]
	v_pk_mul_f32 v[20:21], v[22:23], v[22:23]
	v_add_f32_e32 v18, v18, v19
	v_add_f32_e32 v18, v18, v20
	v_pk_mul_f32 v[16:17], v[16:17], v[16:17]
	v_add_f32_e32 v18, v18, v21
	v_add_f32_e32 v16, v18, v16
	v_pk_mul_f32 v[22:23], v[24:25], v[24:25]
	v_add_f32_e32 v16, v16, v17
	v_add_f32_e32 v16, v16, v22
	v_add_f32_e32 v99, v16, v23
	s_waitcnt vmcnt(11)
	v_and_b32_e32 v21, 0xffff0000, v48
	v_lshlrev_b32_e32 v20, 16, v48
	v_and_b32_e32 v23, 0xffff0000, v49
	v_lshlrev_b32_e32 v22, 16, v49
	v_and_b32_e32 v17, 0xffff0000, v50
	v_lshlrev_b32_e32 v16, 16, v50
	v_and_b32_e32 v25, 0xffff0000, v51
	v_lshlrev_b32_e32 v24, 16, v51
	v_pk_mul_f32 v[18:19], v[20:21], v[20:21]
	v_pk_mul_f32 v[20:21], v[22:23], v[22:23]
	v_add_f32_e32 v18, v18, v19
	v_add_f32_e32 v18, v18, v20
	v_pk_mul_f32 v[16:17], v[16:17], v[16:17]
	v_add_f32_e32 v18, v18, v21
	v_add_f32_e32 v16, v18, v16
	v_pk_mul_f32 v[22:23], v[24:25], v[24:25]
	v_add_f32_e32 v16, v16, v17
	v_add_f32_e32 v16, v16, v22
	v_add_f32_e32 v100, v16, v23
	s_waitcnt vmcnt(10)
	v_and_b32_e32 v21, 0xffff0000, v52
	v_lshlrev_b32_e32 v20, 16, v52
	v_and_b32_e32 v23, 0xffff0000, v53
	v_lshlrev_b32_e32 v22, 16, v53
	v_and_b32_e32 v17, 0xffff0000, v54
	v_lshlrev_b32_e32 v16, 16, v54
	v_and_b32_e32 v25, 0xffff0000, v55
	v_lshlrev_b32_e32 v24, 16, v55
	v_pk_mul_f32 v[18:19], v[20:21], v[20:21]
	v_pk_mul_f32 v[20:21], v[22:23], v[22:23]
	v_add_f32_e32 v18, v18, v19
	v_add_f32_e32 v18, v18, v20
	v_pk_mul_f32 v[16:17], v[16:17], v[16:17]
	v_add_f32_e32 v18, v18, v21
	v_add_f32_e32 v16, v18, v16
	v_pk_mul_f32 v[22:23], v[24:25], v[24:25]
	v_add_f32_e32 v16, v16, v17
	v_add_f32_e32 v16, v16, v22
	v_add_f32_e32 v101, v16, v23
	s_waitcnt vmcnt(9)
	v_and_b32_e32 v21, 0xffff0000, v56
	v_lshlrev_b32_e32 v20, 16, v56
	v_and_b32_e32 v23, 0xffff0000, v57
	v_lshlrev_b32_e32 v22, 16, v57
	v_and_b32_e32 v17, 0xffff0000, v58
	v_lshlrev_b32_e32 v16, 16, v58
	v_and_b32_e32 v25, 0xffff0000, v59
	v_lshlrev_b32_e32 v24, 16, v59
	v_pk_mul_f32 v[18:19], v[20:21], v[20:21]
	v_pk_mul_f32 v[20:21], v[22:23], v[22:23]
	v_add_f32_e32 v18, v18, v19
	v_add_f32_e32 v18, v18, v20
	v_pk_mul_f32 v[16:17], v[16:17], v[16:17]
	v_add_f32_e32 v18, v18, v21
	v_add_f32_e32 v16, v18, v16
	v_pk_mul_f32 v[22:23], v[24:25], v[24:25]
	v_add_f32_e32 v16, v16, v17
	v_add_f32_e32 v16, v16, v22
	v_add_f32_e32 v102, v16, v23
	s_waitcnt vmcnt(8)
	v_and_b32_e32 v21, 0xffff0000, v60
	v_lshlrev_b32_e32 v20, 16, v60
	v_and_b32_e32 v23, 0xffff0000, v61
	v_lshlrev_b32_e32 v22, 16, v61
	v_and_b32_e32 v17, 0xffff0000, v62
	v_lshlrev_b32_e32 v16, 16, v62
	v_and_b32_e32 v25, 0xffff0000, v63
	v_lshlrev_b32_e32 v24, 16, v63
	v_pk_mul_f32 v[18:19], v[20:21], v[20:21]
	v_pk_mul_f32 v[20:21], v[22:23], v[22:23]
	v_add_f32_e32 v18, v18, v19
	v_add_f32_e32 v18, v18, v20
	v_pk_mul_f32 v[16:17], v[16:17], v[16:17]
	v_add_f32_e32 v18, v18, v21
	v_add_f32_e32 v16, v18, v16
	v_pk_mul_f32 v[22:23], v[24:25], v[24:25]
	v_add_f32_e32 v16, v16, v17
	v_add_f32_e32 v16, v16, v22
	v_add_f32_e32 v103, v16, v23
	s_waitcnt vmcnt(7)
	v_and_b32_e32 v21, 0xffff0000, v64
	v_lshlrev_b32_e32 v20, 16, v64
	v_and_b32_e32 v23, 0xffff0000, v65
	v_lshlrev_b32_e32 v22, 16, v65
	v_and_b32_e32 v17, 0xffff0000, v66
	v_lshlrev_b32_e32 v16, 16, v66
	v_and_b32_e32 v25, 0xffff0000, v67
	v_lshlrev_b32_e32 v24, 16, v67
	v_pk_mul_f32 v[18:19], v[20:21], v[20:21]
	v_pk_mul_f32 v[20:21], v[22:23], v[22:23]
	v_add_f32_e32 v18, v18, v19
	v_add_f32_e32 v18, v18, v20
	v_pk_mul_f32 v[16:17], v[16:17], v[16:17]
	v_add_f32_e32 v18, v18, v21
	v_add_f32_e32 v16, v18, v16
	v_pk_mul_f32 v[22:23], v[24:25], v[24:25]
	v_add_f32_e32 v16, v16, v17
	v_add_f32_e32 v16, v16, v22
	v_add_f32_e32 v104, v16, v23
	s_waitcnt vmcnt(6)
	v_and_b32_e32 v21, 0xffff0000, v68
	v_lshlrev_b32_e32 v20, 16, v68
	v_and_b32_e32 v23, 0xffff0000, v69
	v_lshlrev_b32_e32 v22, 16, v69
	v_and_b32_e32 v17, 0xffff0000, v70
	v_lshlrev_b32_e32 v16, 16, v70
	v_and_b32_e32 v25, 0xffff0000, v71
	v_lshlrev_b32_e32 v24, 16, v71
	v_pk_mul_f32 v[18:19], v[20:21], v[20:21]
	v_pk_mul_f32 v[20:21], v[22:23], v[22:23]
	v_add_f32_e32 v18, v18, v19
	v_add_f32_e32 v18, v18, v20
	v_pk_mul_f32 v[16:17], v[16:17], v[16:17]
	v_add_f32_e32 v18, v18, v21
	v_add_f32_e32 v16, v18, v16
	v_pk_mul_f32 v[22:23], v[24:25], v[24:25]
	v_add_f32_e32 v16, v16, v17
	v_add_f32_e32 v16, v16, v22
	v_add_f32_e32 v105, v16, v23
	s_waitcnt vmcnt(5)
	v_and_b32_e32 v21, 0xffff0000, v72
	v_lshlrev_b32_e32 v20, 16, v72
	v_and_b32_e32 v23, 0xffff0000, v73
	v_lshlrev_b32_e32 v22, 16, v73
	v_and_b32_e32 v17, 0xffff0000, v74
	v_lshlrev_b32_e32 v16, 16, v74
	v_and_b32_e32 v25, 0xffff0000, v75
	v_lshlrev_b32_e32 v24, 16, v75
	v_pk_mul_f32 v[18:19], v[20:21], v[20:21]
	v_pk_mul_f32 v[20:21], v[22:23], v[22:23]
	v_add_f32_e32 v18, v18, v19
	v_add_f32_e32 v18, v18, v20
	v_pk_mul_f32 v[16:17], v[16:17], v[16:17]
	v_add_f32_e32 v18, v18, v21
	v_add_f32_e32 v16, v18, v16
	v_pk_mul_f32 v[22:23], v[24:25], v[24:25]
	v_add_f32_e32 v16, v16, v17
	v_add_f32_e32 v16, v16, v22
	v_add_f32_e32 v106, v16, v23
	s_waitcnt vmcnt(4)
	v_and_b32_e32 v21, 0xffff0000, v76
	v_lshlrev_b32_e32 v20, 16, v76
	v_and_b32_e32 v23, 0xffff0000, v77
	v_lshlrev_b32_e32 v22, 16, v77
	v_and_b32_e32 v17, 0xffff0000, v78
	v_lshlrev_b32_e32 v16, 16, v78
	v_and_b32_e32 v25, 0xffff0000, v79
	v_lshlrev_b32_e32 v24, 16, v79
	v_pk_mul_f32 v[18:19], v[20:21], v[20:21]
	v_pk_mul_f32 v[20:21], v[22:23], v[22:23]
	v_add_f32_e32 v18, v18, v19
	v_add_f32_e32 v18, v18, v20
	v_pk_mul_f32 v[16:17], v[16:17], v[16:17]
	v_add_f32_e32 v18, v18, v21
	v_add_f32_e32 v16, v18, v16
	v_pk_mul_f32 v[22:23], v[24:25], v[24:25]
	v_add_f32_e32 v16, v16, v17
	v_add_f32_e32 v16, v16, v22
	v_add_f32_e32 v107, v16, v23
	s_waitcnt vmcnt(3)
	v_and_b32_e32 v21, 0xffff0000, v80
	v_lshlrev_b32_e32 v20, 16, v80
	v_and_b32_e32 v23, 0xffff0000, v81
	v_lshlrev_b32_e32 v22, 16, v81
	v_and_b32_e32 v17, 0xffff0000, v82
	v_lshlrev_b32_e32 v16, 16, v82
	v_and_b32_e32 v25, 0xffff0000, v83
	v_lshlrev_b32_e32 v24, 16, v83
	v_pk_mul_f32 v[18:19], v[20:21], v[20:21]
	v_pk_mul_f32 v[20:21], v[22:23], v[22:23]
	v_add_f32_e32 v18, v18, v19
	v_add_f32_e32 v18, v18, v20
	v_pk_mul_f32 v[16:17], v[16:17], v[16:17]
	v_add_f32_e32 v18, v18, v21
	v_add_f32_e32 v16, v18, v16
	v_pk_mul_f32 v[22:23], v[24:25], v[24:25]
	v_add_f32_e32 v16, v16, v17
	v_add_f32_e32 v16, v16, v22
	v_add_f32_e32 v108, v16, v23
	s_waitcnt vmcnt(2)
	v_and_b32_e32 v21, 0xffff0000, v84
	v_lshlrev_b32_e32 v20, 16, v84
	v_and_b32_e32 v23, 0xffff0000, v85
	v_lshlrev_b32_e32 v22, 16, v85
	v_and_b32_e32 v17, 0xffff0000, v86
	v_lshlrev_b32_e32 v16, 16, v86
	v_and_b32_e32 v25, 0xffff0000, v87
	v_lshlrev_b32_e32 v24, 16, v87
	v_pk_mul_f32 v[18:19], v[20:21], v[20:21]
	v_pk_mul_f32 v[20:21], v[22:23], v[22:23]
	v_add_f32_e32 v18, v18, v19
	v_add_f32_e32 v18, v18, v20
	v_pk_mul_f32 v[16:17], v[16:17], v[16:17]
	v_add_f32_e32 v18, v18, v21
	v_add_f32_e32 v16, v18, v16
	v_pk_mul_f32 v[22:23], v[24:25], v[24:25]
	v_add_f32_e32 v16, v16, v17
	v_add_f32_e32 v16, v16, v22
	v_add_f32_e32 v109, v16, v23
	s_waitcnt vmcnt(1)
	v_and_b32_e32 v21, 0xffff0000, v88
	v_lshlrev_b32_e32 v20, 16, v88
	v_and_b32_e32 v23, 0xffff0000, v89
	v_lshlrev_b32_e32 v22, 16, v89
	v_and_b32_e32 v17, 0xffff0000, v90
	v_lshlrev_b32_e32 v16, 16, v90
	v_and_b32_e32 v25, 0xffff0000, v91
	v_lshlrev_b32_e32 v24, 16, v91
	v_pk_mul_f32 v[18:19], v[20:21], v[20:21]
	v_pk_mul_f32 v[20:21], v[22:23], v[22:23]
	v_add_f32_e32 v18, v18, v19
	v_add_f32_e32 v18, v18, v20
	v_pk_mul_f32 v[16:17], v[16:17], v[16:17]
	v_add_f32_e32 v18, v18, v21
	v_add_f32_e32 v16, v18, v16
	v_pk_mul_f32 v[22:23], v[24:25], v[24:25]
	v_add_f32_e32 v16, v16, v17
	v_add_f32_e32 v16, v16, v22
	v_add_f32_e32 v110, v16, v23
	s_waitcnt vmcnt(0)
	v_and_b32_e32 v21, 0xffff0000, v92
	v_lshlrev_b32_e32 v20, 16, v92
	v_and_b32_e32 v23, 0xffff0000, v93
	v_lshlrev_b32_e32 v22, 16, v93
	v_and_b32_e32 v17, 0xffff0000, v94
	v_lshlrev_b32_e32 v16, 16, v94
	v_and_b32_e32 v25, 0xffff0000, v95
	v_lshlrev_b32_e32 v24, 16, v95
	v_pk_mul_f32 v[18:19], v[20:21], v[20:21]
	v_pk_mul_f32 v[20:21], v[22:23], v[22:23]
	v_add_f32_e32 v18, v18, v19
	v_add_f32_e32 v18, v18, v20
	v_pk_mul_f32 v[16:17], v[16:17], v[16:17]
	v_add_f32_e32 v18, v18, v21
	v_add_f32_e32 v16, v18, v16
	v_pk_mul_f32 v[22:23], v[24:25], v[24:25]
	v_add_f32_e32 v16, v16, v17
	v_add_f32_e32 v16, v16, v22
	v_add_f32_e32 v111, v16, v23
	ds_bpermute_b32 v112, v12, v96
	ds_bpermute_b32 v113, v12, v97
	ds_bpermute_b32 v114, v12, v98
	ds_bpermute_b32 v115, v12, v99
	ds_bpermute_b32 v116, v12, v100
	ds_bpermute_b32 v117, v12, v101
	ds_bpermute_b32 v118, v12, v102
	ds_bpermute_b32 v119, v12, v103
	ds_bpermute_b32 v120, v12, v104
	ds_bpermute_b32 v121, v12, v105
	ds_bpermute_b32 v122, v12, v106
	ds_bpermute_b32 v123, v12, v107
	ds_bpermute_b32 v124, v12, v108
	ds_bpermute_b32 v125, v12, v109
	ds_bpermute_b32 v126, v12, v110
	ds_bpermute_b32 v127, v12, v111
	s_waitcnt lgkmcnt(15)
	v_add_f32_e32 v96, v96, v112
	s_waitcnt lgkmcnt(14)
	v_add_f32_e32 v97, v97, v113
	s_waitcnt lgkmcnt(13)
	v_add_f32_e32 v98, v98, v114
	s_waitcnt lgkmcnt(12)
	v_add_f32_e32 v99, v99, v115
	s_waitcnt lgkmcnt(11)
	v_add_f32_e32 v100, v100, v116
	s_waitcnt lgkmcnt(10)
	v_add_f32_e32 v101, v101, v117
	s_waitcnt lgkmcnt(9)
	v_add_f32_e32 v102, v102, v118
	s_waitcnt lgkmcnt(8)
	v_add_f32_e32 v103, v103, v119
	s_waitcnt lgkmcnt(7)
	v_add_f32_e32 v104, v104, v120
	s_waitcnt lgkmcnt(6)
	v_add_f32_e32 v105, v105, v121
	s_waitcnt lgkmcnt(5)
	v_add_f32_e32 v106, v106, v122
	s_waitcnt lgkmcnt(4)
	v_add_f32_e32 v107, v107, v123
	s_waitcnt lgkmcnt(3)
	v_add_f32_e32 v108, v108, v124
	s_waitcnt lgkmcnt(2)
	v_add_f32_e32 v109, v109, v125
	s_waitcnt lgkmcnt(1)
	v_add_f32_e32 v110, v110, v126
	s_waitcnt lgkmcnt(0)
	v_add_f32_e32 v111, v111, v127
	ds_bpermute_b32 v112, v13, v96
	ds_bpermute_b32 v113, v13, v97
	ds_bpermute_b32 v114, v13, v98
	ds_bpermute_b32 v115, v13, v99
	ds_bpermute_b32 v116, v13, v100
	ds_bpermute_b32 v117, v13, v101
	ds_bpermute_b32 v118, v13, v102
	ds_bpermute_b32 v119, v13, v103
	ds_bpermute_b32 v120, v13, v104
	ds_bpermute_b32 v121, v13, v105
	ds_bpermute_b32 v122, v13, v106
	ds_bpermute_b32 v123, v13, v107
	ds_bpermute_b32 v124, v13, v108
	ds_bpermute_b32 v125, v13, v109
	ds_bpermute_b32 v126, v13, v110
	ds_bpermute_b32 v127, v13, v111
	s_waitcnt lgkmcnt(15)
	v_add_f32_e32 v96, v96, v112
	s_waitcnt lgkmcnt(14)
	v_add_f32_e32 v97, v97, v113
	s_waitcnt lgkmcnt(13)
	v_add_f32_e32 v98, v98, v114
	s_waitcnt lgkmcnt(12)
	v_add_f32_e32 v99, v99, v115
	s_waitcnt lgkmcnt(11)
	v_add_f32_e32 v100, v100, v116
	s_waitcnt lgkmcnt(10)
	v_add_f32_e32 v101, v101, v117
	s_waitcnt lgkmcnt(9)
	v_add_f32_e32 v102, v102, v118
	s_waitcnt lgkmcnt(8)
	v_add_f32_e32 v103, v103, v119
	s_waitcnt lgkmcnt(7)
	v_add_f32_e32 v104, v104, v120
	s_waitcnt lgkmcnt(6)
	v_add_f32_e32 v105, v105, v121
	s_waitcnt lgkmcnt(5)
	v_add_f32_e32 v106, v106, v122
	s_waitcnt lgkmcnt(4)
	v_add_f32_e32 v107, v107, v123
	s_waitcnt lgkmcnt(3)
	v_add_f32_e32 v108, v108, v124
	s_waitcnt lgkmcnt(2)
	v_add_f32_e32 v109, v109, v125
	s_waitcnt lgkmcnt(1)
	v_add_f32_e32 v110, v110, v126
	s_waitcnt lgkmcnt(0)
	v_add_f32_e32 v111, v111, v127
	ds_bpermute_b32 v112, v15, v96
	ds_bpermute_b32 v113, v15, v97
	ds_bpermute_b32 v114, v15, v98
	ds_bpermute_b32 v115, v15, v99
	ds_bpermute_b32 v116, v15, v100
	ds_bpermute_b32 v117, v15, v101
	ds_bpermute_b32 v118, v15, v102
	ds_bpermute_b32 v119, v15, v103
	ds_bpermute_b32 v120, v15, v104
	ds_bpermute_b32 v121, v15, v105
	ds_bpermute_b32 v122, v15, v106
	ds_bpermute_b32 v123, v15, v107
	ds_bpermute_b32 v124, v15, v108
	ds_bpermute_b32 v125, v15, v109
	ds_bpermute_b32 v126, v15, v110
	ds_bpermute_b32 v127, v15, v111
	s_waitcnt lgkmcnt(15)
	v_add_f32_e32 v96, v96, v112
	s_waitcnt lgkmcnt(14)
	v_add_f32_e32 v97, v97, v113
	s_waitcnt lgkmcnt(13)
	v_add_f32_e32 v98, v98, v114
	s_waitcnt lgkmcnt(12)
	v_add_f32_e32 v99, v99, v115
	s_waitcnt lgkmcnt(11)
	v_add_f32_e32 v100, v100, v116
	s_waitcnt lgkmcnt(10)
	v_add_f32_e32 v101, v101, v117
	s_waitcnt lgkmcnt(9)
	v_add_f32_e32 v102, v102, v118
	s_waitcnt lgkmcnt(8)
	v_add_f32_e32 v103, v103, v119
	s_waitcnt lgkmcnt(7)
	v_add_f32_e32 v104, v104, v120
	s_waitcnt lgkmcnt(6)
	v_add_f32_e32 v105, v105, v121
	s_waitcnt lgkmcnt(5)
	v_add_f32_e32 v106, v106, v122
	s_waitcnt lgkmcnt(4)
	v_add_f32_e32 v107, v107, v123
	s_waitcnt lgkmcnt(3)
	v_add_f32_e32 v108, v108, v124
	s_waitcnt lgkmcnt(2)
	v_add_f32_e32 v109, v109, v125
	s_waitcnt lgkmcnt(1)
	v_add_f32_e32 v110, v110, v126
	s_waitcnt lgkmcnt(0)
	v_add_f32_e32 v111, v111, v127
	v_max_f32_e32 v14, v14, v96
	v_max_f32_e32 v14, v14, v97
	v_max_f32_e32 v14, v14, v98
	v_max_f32_e32 v14, v14, v99
	v_max_f32_e32 v14, v14, v100
	v_max_f32_e32 v14, v14, v101
	v_max_f32_e32 v14, v14, v102
	v_max_f32_e32 v14, v14, v103
	v_max_f32_e32 v14, v14, v104
	v_max_f32_e32 v14, v14, v105
	v_max_f32_e32 v14, v14, v106
	v_max_f32_e32 v14, v14, v107
	v_max_f32_e32 v14, v14, v108
	v_max_f32_e32 v14, v14, v109
	v_max_f32_e32 v14, v14, v110
	v_max_f32_e32 v14, v14, v111
	v_cmp_lt_i32_e32 vcc, v209, v206
	s_nop 1
	v_cndmask_b32_e32 v6, v205, v209, vcc
	v_lshlrev_b32_e32 v6, 2, v6
	ds_bpermute_b32 v6, v6, v14
	s_and_saveexec_b64 s[36:37], s[0:1]
	s_cbranch_execz .LBB0_1303
	s_waitcnt lgkmcnt(0)
	v_max_f32_e32 v6, v6, v6
	v_max_f32_e32 v7, v14, v14
	v_max_f32_e32 v6, v7, v6
	ds_write_b32 v0, v6
